# phase 0: silu(c) staging loop rewritten as 6 batches of 8 loads (was 48 serialized load-wait iterations); first-barrier census polls batched
# speedup vs baseline: 1.0133x; 1.0043x over previous
.LBB0_316:
	s_and_b64 vcc, exec, s[0:1]
	s_cbranch_vccz .LBB0_372
	s_movk_i32 s0, 0x6000
	v_cmp_gt_i32_e32 vcc, s0, v168
	s_and_saveexec_b64 s[0:1], vcc
	s_cbranch_execz .LBB0_322
	v_readlane_b32 s36, v253, 8
	v_ashrrev_i32_e32 v169, 31, v168
	v_readlane_b32 s40, v253, 12
	v_readlane_b32 s41, v253, 13
	v_readlane_b32 s44, v253, 16
	s_mov_b32 s44, s63
	v_lshl_add_u64 v[2:3], v[168:169], 2, s[40:41]
	s_mov_b64 s[12:13], 0
	v_mov_b32_e32 v1, v168
	v_readlane_b32 s37, v253, 9
	v_readlane_b32 s38, v253, 10
	v_readlane_b32 s39, v253, 11
	v_readlane_b32 s42, v253, 14
	v_readlane_b32 s43, v253, 15
	v_readlane_b32 s45, v253, 17
	v_readlane_b32 s46, v253, 18
	v_readlane_b32 s47, v253, 19
	v_readlane_b32 s48, v253, 20
	v_readlane_b32 s49, v253, 21
	v_readlane_b32 s50, v253, 22
	v_readlane_b32 s51, v253, 23
	v_lshlrev_b32_e32 v2, 2, v168
	v_mul_u32_u24_e32 v1, 0x60, v168
	s_mov_b32 s12, 0
	s_mov_b64 s[14:15], s[40:41]
.Lsilu_batch:
	s_cmp_eq_u32 s12, 4
	s_cselect_b32 s14, s42, s14
	s_cselect_b32 s15, s43, s15
	global_load_dword v12, v2, s[14:15]
	global_load_dword v13, v2, s[14:15] offset:2048
	s_add_u32 s14, s14, 0x1000
	s_addc_u32 s15, s15, 0
	global_load_dword v14, v2, s[14:15]
	global_load_dword v15, v2, s[14:15] offset:2048
	s_add_u32 s14, s14, 0x1000
	s_addc_u32 s15, s15, 0
	global_load_dword v16, v2, s[14:15]
	global_load_dword v17, v2, s[14:15] offset:2048
	s_add_u32 s14, s14, 0x1000
	s_addc_u32 s15, s15, 0
	global_load_dword v18, v2, s[14:15]
	global_load_dword v19, v2, s[14:15] offset:2048
	s_add_u32 s14, s14, 0x1000
	s_addc_u32 s15, s15, 0
	s_waitcnt vmcnt(0)
	v_mov_b32_e32 v4, v12
	v_mul_f32_e32 v8, 0xbfb8aa3b, v4
	v_exp_f32_e32 v8, v8
	s_nop 0
	v_add_f32_e32 v5, 1.0, v8
	v_div_scale_f32 v6, s[2:3], v5, v5, v4
	v_rcp_f32_e32 v8, v6
	v_div_scale_f32 v9, vcc, v4, v5, v4
	v_fma_f32 v10, -v6, v8, 1.0
	v_fmac_f32_e32 v8, v10, v8
	v_mul_f32_e32 v10, v9, v8
	v_fma_f32 v11, -v6, v10, v9
	v_fmac_f32_e32 v10, v11, v8
	v_fma_f32 v6, -v6, v10, v9
	v_div_fmas_f32 v6, v6, v8, v10
	v_div_fixup_f32 v4, v6, v5, v4
	ds_write_b32 v1, v4
	v_mov_b32_e32 v4, v13
	v_mul_f32_e32 v8, 0xbfb8aa3b, v4
	v_exp_f32_e32 v8, v8
	s_nop 0
	v_add_f32_e32 v5, 1.0, v8
	v_div_scale_f32 v6, s[2:3], v5, v5, v4
	v_rcp_f32_e32 v8, v6
	v_div_scale_f32 v9, vcc, v4, v5, v4
	v_fma_f32 v10, -v6, v8, 1.0
	v_fmac_f32_e32 v8, v10, v8
	v_mul_f32_e32 v10, v9, v8
	v_fma_f32 v11, -v6, v10, v9
	v_fmac_f32_e32 v10, v11, v8
	v_fma_f32 v6, -v6, v10, v9
	v_div_fmas_f32 v6, v6, v8, v10
	v_div_fixup_f32 v4, v6, v5, v4
	ds_write_b32 v1, v4 offset:49152
	v_mov_b32_e32 v4, v14
	v_mul_f32_e32 v8, 0xbfb8aa3b, v4
	v_exp_f32_e32 v8, v8
	s_nop 0
	v_add_f32_e32 v5, 1.0, v8
	v_div_scale_f32 v6, s[2:3], v5, v5, v4
	v_rcp_f32_e32 v8, v6
	v_div_scale_f32 v9, vcc, v4, v5, v4
	v_fma_f32 v10, -v6, v8, 1.0
	v_fmac_f32_e32 v8, v10, v8
	v_mul_f32_e32 v10, v9, v8
	v_fma_f32 v11, -v6, v10, v9
	v_fmac_f32_e32 v10, v11, v8
	v_fma_f32 v6, -v6, v10, v9
	v_div_fmas_f32 v6, v6, v8, v10
	v_div_fixup_f32 v4, v6, v5, v4
	ds_write_b32 v1, v4 offset:4
	v_mov_b32_e32 v4, v15
	v_mul_f32_e32 v8, 0xbfb8aa3b, v4
	v_exp_f32_e32 v8, v8
	s_nop 0
	v_add_f32_e32 v5, 1.0, v8
	v_div_scale_f32 v6, s[2:3], v5, v5, v4
	v_rcp_f32_e32 v8, v6
	v_div_scale_f32 v9, vcc, v4, v5, v4
	v_fma_f32 v10, -v6, v8, 1.0
	v_fmac_f32_e32 v8, v10, v8
	v_mul_f32_e32 v10, v9, v8
	v_fma_f32 v11, -v6, v10, v9
	v_fmac_f32_e32 v10, v11, v8
	v_fma_f32 v6, -v6, v10, v9
	v_div_fmas_f32 v6, v6, v8, v10
	v_div_fixup_f32 v4, v6, v5, v4
	ds_write_b32 v1, v4 offset:49156
	v_mov_b32_e32 v4, v16
	v_mul_f32_e32 v8, 0xbfb8aa3b, v4
	v_exp_f32_e32 v8, v8
	s_nop 0
	v_add_f32_e32 v5, 1.0, v8
	v_div_scale_f32 v6, s[2:3], v5, v5, v4
	v_rcp_f32_e32 v8, v6
	v_div_scale_f32 v9, vcc, v4, v5, v4
	v_fma_f32 v10, -v6, v8, 1.0
	v_fmac_f32_e32 v8, v10, v8
	v_mul_f32_e32 v10, v9, v8
	v_fma_f32 v11, -v6, v10, v9
	v_fmac_f32_e32 v10, v11, v8
	v_fma_f32 v6, -v6, v10, v9
	v_div_fmas_f32 v6, v6, v8, v10
	v_div_fixup_f32 v4, v6, v5, v4
	ds_write_b32 v1, v4 offset:8
	v_mov_b32_e32 v4, v17
	v_mul_f32_e32 v8, 0xbfb8aa3b, v4
	v_exp_f32_e32 v8, v8
	s_nop 0
	v_add_f32_e32 v5, 1.0, v8
	v_div_scale_f32 v6, s[2:3], v5, v5, v4
	v_rcp_f32_e32 v8, v6
	v_div_scale_f32 v9, vcc, v4, v5, v4
	v_fma_f32 v10, -v6, v8, 1.0
	v_fmac_f32_e32 v8, v10, v8
	v_mul_f32_e32 v10, v9, v8
	v_fma_f32 v11, -v6, v10, v9
	v_fmac_f32_e32 v10, v11, v8
	v_fma_f32 v6, -v6, v10, v9
	v_div_fmas_f32 v6, v6, v8, v10
	v_div_fixup_f32 v4, v6, v5, v4
	ds_write_b32 v1, v4 offset:49160
	v_mov_b32_e32 v4, v18
	v_mul_f32_e32 v8, 0xbfb8aa3b, v4
	v_exp_f32_e32 v8, v8
	s_nop 0
	v_add_f32_e32 v5, 1.0, v8
	v_div_scale_f32 v6, s[2:3], v5, v5, v4
	v_rcp_f32_e32 v8, v6
	v_div_scale_f32 v9, vcc, v4, v5, v4
	v_fma_f32 v10, -v6, v8, 1.0
	v_fmac_f32_e32 v8, v10, v8
	v_mul_f32_e32 v10, v9, v8
	v_fma_f32 v11, -v6, v10, v9
	v_fmac_f32_e32 v10, v11, v8
	v_fma_f32 v6, -v6, v10, v9
	v_div_fmas_f32 v6, v6, v8, v10
	v_div_fixup_f32 v4, v6, v5, v4
	ds_write_b32 v1, v4 offset:12
	v_mov_b32_e32 v4, v19
	v_mul_f32_e32 v8, 0xbfb8aa3b, v4
	v_exp_f32_e32 v8, v8
	s_nop 0
	v_add_f32_e32 v5, 1.0, v8
	v_div_scale_f32 v6, s[2:3], v5, v5, v4
	v_rcp_f32_e32 v8, v6
	v_div_scale_f32 v9, vcc, v4, v5, v4
	v_fma_f32 v10, -v6, v8, 1.0
	v_fmac_f32_e32 v8, v10, v8
	v_mul_f32_e32 v10, v9, v8
	v_fma_f32 v11, -v6, v10, v9
	v_fmac_f32_e32 v10, v11, v8
	v_fma_f32 v6, -v6, v10, v9
	v_div_fmas_f32 v6, v6, v8, v10
	v_div_fixup_f32 v4, v6, v5, v4
	ds_write_b32 v1, v4 offset:49164
	v_add_u32_e32 v1, 16, v1
	s_add_i32 s12, s12, 1
	s_cmp_lt_u32 s12, 6
	s_cbranch_scc1 .Lsilu_batch

.LBB0_376:
	v_readlane_b32 s8, v253, 43
	v_readlane_b32 s9, v253, 44
	global_load_dword v1, v0, s[54:55] sc1
	s_mov_b64 s[12:13], -1
	s_mov_b64 s[14:15], -1
	s_waitcnt lgkmcnt(0)
	s_nop 0
	global_load_dword v2, v0, s[8:9] sc1
	v_readlane_b32 s8, v253, 45
	v_readlane_b32 s9, v253, 46
	s_nop 1
	s_nop 2
	global_load_dword v3, v0, s[8:9] sc1
	v_readlane_b32 s8, v253, 47
	v_readlane_b32 s9, v253, 48
	s_nop 1
	s_nop 2
	global_load_dword v4, v0, s[8:9] sc1
	v_readlane_b32 s8, v253, 49
	v_readlane_b32 s9, v253, 50
	s_nop 1
	s_nop 2
	global_load_dword v5, v0, s[8:9] sc1
	v_readlane_b32 s8, v253, 51
	v_readlane_b32 s9, v253, 52
	s_nop 1
	s_nop 2
	global_load_dword v6, v0, s[8:9] sc1
	v_readlane_b32 s8, v253, 53
	v_readlane_b32 s9, v253, 54
	s_nop 1
	s_nop 2
	global_load_dword v7, v0, s[8:9] sc1
	v_readlane_b32 s8, v253, 55
	v_readlane_b32 s9, v253, 56
	s_nop 1
	s_nop 2
	global_load_dword v8, v0, s[8:9] sc1
	v_readlane_b32 s8, v253, 57
	v_readlane_b32 s9, v253, 58
	s_nop 1
	s_nop 2
	global_load_dword v9, v0, s[8:9] sc1
	v_readlane_b32 s8, v253, 59
	v_readlane_b32 s9, v253, 60
	s_nop 1
	s_nop 2
	global_load_dword v10, v0, s[8:9] sc1
	v_readlane_b32 s8, v253, 61
	v_readlane_b32 s9, v253, 62
	s_nop 1
	s_nop 2
	global_load_dword v11, v0, s[8:9] sc1
	v_readlane_b32 s8, v253, 63
	v_readlane_b32 s9, v254, 0
	s_nop 1
	s_nop 2
	global_load_dword v12, v0, s[8:9] sc1
	v_readlane_b32 s8, v254, 1
	v_readlane_b32 s9, v254, 2
	s_nop 1
	s_nop 2
	global_load_dword v13, v0, s[8:9] sc1
	v_readlane_b32 s8, v254, 3
	v_readlane_b32 s9, v254, 4
	s_nop 1
	s_nop 2
	global_load_dword v14, v0, s[8:9] sc1
	v_readlane_b32 s8, v254, 5
	v_readlane_b32 s9, v254, 6
	s_nop 1
	s_nop 2
	global_load_dword v15, v0, s[8:9] sc1
	v_readlane_b32 s8, v254, 7
	v_readlane_b32 s9, v254, 8
	s_nop 1
	s_nop 2
	global_load_dword v16, v0, s[8:9] sc1
	s_nop 1
	s_waitcnt vmcnt(0)
	v_add_u32_e32 v17, v2, v1
	v_add_u32_e32 v17, v17, v3
	v_add_u32_e32 v17, v17, v4
	v_add_u32_e32 v17, v17, v5
	v_add_u32_e32 v17, v17, v6
	v_add_u32_e32 v17, v17, v7
	v_add_u32_e32 v17, v17, v8
	v_add_u32_e32 v17, v17, v9
	v_add_u32_e32 v17, v17, v10
	v_add_u32_e32 v17, v17, v11
	v_add_u32_e32 v17, v17, v12
	v_add_u32_e32 v17, v17, v13
	v_add_u32_e32 v17, v17, v14
	v_add_u32_e32 v17, v17, v15
	v_add_u32_e32 v17, v17, v16
	v_cmp_eq_u32_e32 vcc, s81, v17
	s_cbranch_vccnz .LBB0_375
	s_and_b32 s3, s2, 0xff
	s_cmp_eq_u32 s3, 0
	s_mov_b64 s[20:21], -1
	s_sleep 1
	s_cbranch_scc1 .LBB0_380
	s_and_b64 vcc, exec, s[20:21]
	s_cbranch_vccz .LBB0_375
